# down-proj layer-0 tail split remapped (unit = bid&15, split = bid>>4): consumers are CUs 0..15 which carry no layer-1 weight-transpose share
# baseline (speedup 1.0000x reference)
;     __device__ __forceinline__ bool next(int i, Unit& u) const {
;         constexpr int NU = (33792 / BM) * NN;
;         const int L = i * G + ((NU - i * G < G) ? vp : v); if (L >= NU) return false;
;         constexpr int NM = 33792 / BM, NFULL = (NM / 8) * 8 * NN;
;         if (L < NFULL) { const int g = L / (8 * NN), idx = L % (8 * NN); u.pm = g * 8 + (idx & 7); u.pn = idx >> 3; }
;         else { constexpr int GS = NM % 8 ? NM % 8 : 8; const int idx = L - NFULL; u.pm = (NM / 8) * 8 + idx % GS; u.pn = idx / GS; }
;         return true;
;     }
; template <int KK, class Epi, class Sched, bool ALIGN_EPI = true>
; __device__ __forceinline__ void gemm_phase(LAS unsigned char* lds, const bf16* gA, const bf16* gBt, const Sched& S, const Epi& E, const int wid) {
;     ...
;         const bool has_next = S.next(ui + 1, nxt);
.LBB0_661:
	s_add_i32 s41, s41, 1
	s_mul_i32 s6, s41, s64
	s_sub_i32 s7, 0x210, s6
	s_cmp_lt_i32 s7, s64
	s_cselect_b32 s18, s0, s1
	s_add_i32 s18, s18, s6
	s_cmp_lg_u32 s64, 0x100
	s_cbranch_scc1 .Lp5a_sch
	s_cmp_lg_u32 s41, 2
	s_cbranch_scc1 .Lp5a_sch
	s_movk_i32 s18, 0x210
	s_cmp_gt_u32 s86, 63
	s_cbranch_scc1 .Lp5a_sch
	s_and_b32 s18, s86, 15
	s_addk_i32 s18, 0x200

; #define PG8_STAGE(bufoff, gbase, voff) do { _Pragma("unroll") for (int _i = 0; _i < 2; ++_i) \
;         __builtin_amdgcn_global_load_lds((const unsigned*)((const char*)(gbase) + (voff)[_i]), (LAS unsigned*)(lds + (bufoff) + ldsw + _i * 8192), 16, 0, 0); } while (0)
; #define PG8_WAIT_V(n) asm volatile("s_waitcnt vmcnt(" #n ")" ::: "memory")
; #define PG8_BAR __builtin_amdgcn_s_barrier()
; template <int KK, class Epi, class Sched, bool ALIGN_EPI = true>
; __device__ __forceinline__ void gemm_phase(LAS unsigned char* lds, const bf16* gA, const bf16* gBt, const Sched& S, const Epi& E, const int wid) {
;     ...
;     const char* cA = (const char*)gA + (size_t)cur.pm * tstep; const char* cB = (const char*)gBt + (size_t)cur.pn * tstep;
;     PG8_STAGE(PG8_SB(0, 0), cB, voffB); PG8_STAGE(PG8_SB(0, 1), cB + hstep, voffB); PG8_STAGE(PG8_SA(0, 0), cA, voffA); PG8_STAGE(PG8_SA(0, 1), cA + hstep, voffA);
;     PG8_STAGE(PG8_SB(1, 0), cB + kstep, voffB); PG8_STAGE(PG8_SA(1, 0), cA + kstep, voffA); PG8_STAGE(PG8_SB(1, 1), cB + hstep + kstep, voffB);
;     if (wr == 1) PG8_BAR;
;     PG8_WAIT_V(8); PG8_BAR;
;     PG8_WAIT_V(6); PG8_BAR;
;     for (;;) {
;         const bool has_next = S.next(ui + 1, nxt);
;         const char* nA = has_next ? (const char*)gA + (size_t)nxt.pm * tstep : cA; const char* nB = has_next ? (const char*)gBt + (size_t)nxt.pn * tstep : cB;
; #pragma unroll 1
;         for (int t = 0; t < nt; t += 2) {
;             const bool last = (t == nt - 2);
;             const char* a1 = cA + (size_t)(t + 1) * kstep;
;             const char* a2 = last ? nA : cA + (size_t)(t + 2) * kstep; const char* b2 = last ? nB : cB + (size_t)(t + 2) * kstep;
;             const char* a3 = a2 + kstep; const char* b3 = b2 + kstep;
.LBB0_670:
	s_cmp_lg_u32 s64, 0x100
	s_cbranch_scc1 .Lp5a_kof
	s_cmp_lg_u32 s41, 2
	s_cbranch_scc1 .Lp5a_kof
	s_cmp_gt_u32 s86, 63
	s_cbranch_scc1 .Lp5a_kof
	s_lshr_b32 s82, s86, 4
	s_mul_i32 s83, s82, 0x600
	s_cmp_eq_u32 s82, 3
	s_cselect_b32 s82, 0x100, 0
	s_sub_i32 s83, s83, s82
	s_add_u32 s16, s16, s83
	s_addc_u32 s17, s17, 0
	s_add_u32 s18, s18, s83
	s_addc_u32 s19, s19, 0
.Lp5a_kof:
	s_add_u32 s69, s42, 0x100
	v_mov_b32_e32 v0, 0
	s_addc_u32 s70, s43, 0
	s_mov_b32 s71, -2
	s_cmp_lg_u32 s64, 0x100
	s_cbranch_scc1 .Lp5a_cnt
	s_cmp_lg_u32 s41, 3
	s_cbranch_scc1 .Lp5a_cnt
	s_bfe_u32 s82, s86, 0x10005
	s_lshl_b32 s82, s82, 1
	s_add_i32 s71, s82, 30

; #define PG8_BAR __builtin_amdgcn_s_barrier()
; template <int KK, class Epi, class Sched, bool ALIGN_EPI = true>
; __device__ __forceinline__ void gemm_phase(LAS unsigned char* lds, const bf16* gA, const bf16* gBt, const Sched& S, const Epi& E, const int wid) {
;     ...
;         if constexpr (ALIGN_EPI) { if (wr == 0) PG8_BAR; }
;         E(acc, cur, wr, wc, fr, fq);
;         if (!has_next) break;
.LBB0_674:
	s_cmp_lg_u32 s64, 0x100
	s_cbranch_scc1 .Lp5a_epi
	s_cmp_lg_u32 s41, 3
	s_cbranch_scc1 .Lp5a_epi
	s_lshr_b32 s32, s86, 4
	s_and_b32 s90, s86, 15
	v_readlane_b32 s88, v249, 0
	v_lshlrev_b32_e32 v140, 4, v196
	s_nop 1
	s_lshl_b32 s89, s88, 10
	v_add_u32_e32 v140, s89, v140
	s_mul_i32 s89, s90, 3
	s_lshl_b32 s89, s89, 18
	s_add_u32 s76, s46, s89
	s_addc_u32 s77, s47, 0
	s_add_u32 s76, s76, 0x0
	s_addc_u32 s77, s77, 0
	s_cmp_eq_u32 s32, 0
	s_cbranch_scc1 .Lp5a_cons
	s_add_i32 s89, s32, -1
	s_lshl_b32 s89, s89, 18
	s_add_u32 s76, s76, s89
	s_addc_u32 s77, s77, 0
	s_nop 7
	global_store_dwordx4 v140, v[0:3], s[76:77] sc0 sc1
	s_add_u32 s76, s76, 0x2000
	s_addc_u32 s77, s77, 0
	global_store_dwordx4 v140, v[4:7], s[76:77] sc0 sc1
	s_add_u32 s76, s76, 0x2000
	s_addc_u32 s77, s77, 0
	global_store_dwordx4 v140, v[8:11], s[76:77] sc0 sc1
	s_add_u32 s76, s76, 0x2000
	s_addc_u32 s77, s77, 0
	global_store_dwordx4 v140, v[12:15], s[76:77] sc0 sc1
	s_add_u32 s76, s76, 0x2000
	s_addc_u32 s77, s77, 0
	global_store_dwordx4 v140, v[16:19], s[76:77] sc0 sc1
	s_add_u32 s76, s76, 0x2000
	s_addc_u32 s77, s77, 0
	global_store_dwordx4 v140, v[20:23], s[76:77] sc0 sc1
	s_add_u32 s76, s76, 0x2000
	s_addc_u32 s77, s77, 0
	global_store_dwordx4 v140, v[24:27], s[76:77] sc0 sc1
	s_add_u32 s76, s76, 0x2000
	s_addc_u32 s77, s77, 0
	global_store_dwordx4 v140, v[28:31], s[76:77] sc0 sc1
	s_add_u32 s76, s76, 0x2000
	s_addc_u32 s77, s77, 0
	global_store_dwordx4 v140, v[32:35], s[76:77] sc0 sc1
	s_add_u32 s76, s76, 0x2000
	s_addc_u32 s77, s77, 0
	global_store_dwordx4 v140, v[36:39], s[76:77] sc0 sc1
	s_add_u32 s76, s76, 0x2000
	s_addc_u32 s77, s77, 0
	global_store_dwordx4 v140, v[40:43], s[76:77] sc0 sc1
	s_add_u32 s76, s76, 0x2000
	s_addc_u32 s77, s77, 0
	global_store_dwordx4 v140, v[44:47], s[76:77] sc0 sc1
	s_add_u32 s76, s76, 0x2000
	s_addc_u32 s77, s77, 0
	global_store_dwordx4 v140, v[48:51], s[76:77] sc0 sc1
	s_add_u32 s76, s76, 0x2000
	s_addc_u32 s77, s77, 0
	global_store_dwordx4 v140, v[52:55], s[76:77] sc0 sc1
	s_add_u32 s76, s76, 0x2000
	s_addc_u32 s77, s77, 0
	global_store_dwordx4 v140, v[56:59], s[76:77] sc0 sc1
	s_add_u32 s76, s76, 0x2000
	s_addc_u32 s77, s77, 0
	global_store_dwordx4 v140, v[60:63], s[76:77] sc0 sc1
	s_add_u32 s76, s76, 0x2000
	s_addc_u32 s77, s77, 0
	global_store_dwordx4 v140, v[64:67], s[76:77] sc0 sc1
	s_add_u32 s76, s76, 0x2000
	s_addc_u32 s77, s77, 0
	global_store_dwordx4 v140, v[68:71], s[76:77] sc0 sc1
	s_add_u32 s76, s76, 0x2000
	s_addc_u32 s77, s77, 0
	global_store_dwordx4 v140, v[72:75], s[76:77] sc0 sc1
	s_add_u32 s76, s76, 0x2000
	s_addc_u32 s77, s77, 0
	global_store_dwordx4 v140, v[76:79], s[76:77] sc0 sc1
	s_add_u32 s76, s76, 0x2000
	s_addc_u32 s77, s77, 0
	global_store_dwordx4 v140, v[80:83], s[76:77] sc0 sc1
	s_add_u32 s76, s76, 0x2000
	s_addc_u32 s77, s77, 0
	global_store_dwordx4 v140, v[84:87], s[76:77] sc0 sc1
	s_add_u32 s76, s76, 0x2000
	s_addc_u32 s77, s77, 0
	global_store_dwordx4 v140, v[88:91], s[76:77] sc0 sc1
	s_add_u32 s76, s76, 0x2000
	s_addc_u32 s77, s77, 0
	global_store_dwordx4 v140, v[92:95], s[76:77] sc0 sc1
	s_add_u32 s76, s76, 0x2000
	s_addc_u32 s77, s77, 0
	global_store_dwordx4 v140, v[96:99], s[76:77] sc0 sc1
	s_add_u32 s76, s76, 0x2000
	s_addc_u32 s77, s77, 0
	global_store_dwordx4 v140, v[100:103], s[76:77] sc0 sc1
	s_add_u32 s76, s76, 0x2000
	s_addc_u32 s77, s77, 0
	global_store_dwordx4 v140, v[104:107], s[76:77] sc0 sc1
	s_add_u32 s76, s76, 0x2000
	s_addc_u32 s77, s77, 0
	global_store_dwordx4 v140, v[108:111], s[76:77] sc0 sc1
	s_add_u32 s76, s76, 0x2000
	s_addc_u32 s77, s77, 0
	global_store_dwordx4 v140, v[112:115], s[76:77] sc0 sc1
	s_add_u32 s76, s76, 0x2000
	s_addc_u32 s77, s77, 0
	global_store_dwordx4 v140, v[116:119], s[76:77] sc0 sc1
	s_add_u32 s76, s76, 0x2000
	s_addc_u32 s77, s77, 0
	global_store_dwordx4 v140, v[120:123], s[76:77] sc0 sc1
	s_add_u32 s76, s76, 0x2000
	s_addc_u32 s77, s77, 0
	global_store_dwordx4 v140, v[124:127], s[76:77] sc0 sc1
	s_waitcnt vmcnt(0)
	s_lshl_b32 s89, s90, 2
	s_add_i32 s89, s89, s32
	s_lshl_b32 s89, s89, 2
	v_mov_b32_e32 v141, s89
	v_mov_b32_e32 v142, 1
	s_mov_b64 s[78:79], exec
	s_mov_b64 exec, 1
	global_atomic_add v141, v142, s[44:45] offset:3200
	s_mov_b64 exec, s[78:79]
	s_branch .LBB0_677
